# fast barrier: fire-and-forget arrival + direct counter poll (one hop less); designated WG per XCD publishes for split seams
# baseline (speedup 1.0000x reference)
.LBB0_99:
	s_or_b64 exec, exec, s[2:3]
	s_barrier
	v_readlane_b32 s0, v255, 0
	v_readlane_b32 s1, v255, 1
	s_nop 4
	s_load_dword s2, s[0:1], 0x100
	s_load_dwordx2 s[4:5], s[0:1], 0xf0
	s_getreg_b32 s3, hwreg(HW_REG_XCC_ID, 0, 4)
	s_and_b32 s3, s3, 15
	s_lshl_b32 s3, s3, 8
	v_and_b32_e32 v2, 7, v218
	v_lshlrev_b32_e32 v2, 2, v2
	s_waitcnt lgkmcnt(0)
	s_add_u32 s4, s4, 0x14000
	s_addc_u32 s5, s5, 0
	s_nop 1
	global_load_dword v3, v2, s[4:5] offset:64 sc1
	global_load_dword v4, v2, s[4:5] offset:128 sc1
	s_waitcnt vmcnt(0)
	v_add_u32_e32 v4, v3, v4
	v_cmp_ne_u32_e32 vcc, 17, v4
	v_add_u32_e32 v3, -1, v3
	v_lshlrev_b32_e64 v3, v3, 1
	s_nop 1
	v_readlane_b32 s1, v3, 0
	v_readlane_b32 s0, v3, 1
	s_nop 1
	s_or_b32 s1, s1, s0
	v_readlane_b32 s0, v3, 2
	s_nop 1
	s_or_b32 s1, s1, s0
	v_readlane_b32 s0, v3, 3
	s_nop 1
	s_or_b32 s1, s1, s0
	v_readlane_b32 s0, v3, 4
	s_nop 1
	s_or_b32 s1, s1, s0
	v_readlane_b32 s0, v3, 5
	s_nop 1
	s_or_b32 s1, s1, s0
	v_readlane_b32 s0, v3, 6
	s_nop 1
	s_or_b32 s1, s1, s0
	v_readlane_b32 s0, v3, 7
	s_nop 1
	s_or_b32 s1, s1, s0
	s_bcnt1_i32_b32 s0, s1
	s_add_u32 s4, s4, s3
	s_addc_u32 s5, s5, 0
	s_add_u32 s4, s4, 0x100
	s_addc_u32 s5, s5, 0
	s_cmp_eq_u32 s0, 8
	s_cselect_b32 s1, 32, 0
	s_cmp_eq_u64 vcc, 0
	s_cselect_b32 s1, s1, 0
	s_cmpk_eq_u32 s2, 0x100
	s_cselect_b32 s1, s1, 0
	s_mov_b32 s0, 0
	v_writelane_b32 v255, s0, 47
	v_writelane_b32 v255, s1, 40
	v_writelane_b32 v255, s4, 41
	v_writelane_b32 v255, s5, 42
	s_sub_u32 s4, s4, s3
	s_subb_u32 s5, s5, 0
	s_sub_u32 s4, s4, 0xe0
	s_subb_u32 s5, s5, 0
	v_writelane_b32 v255, s4, 45
	v_writelane_b32 v255, s5, 46
	s_mov_b32 s4, 0
	v_writelane_b32 v255, s4, 43
	v_writelane_b32 v255, s4, 44
	v_writelane_b32 v255, s4, 47
	s_load_dword s0, s[78:79], 0x108
	s_add_i32 s2, 0, 0x1c800
	v_writelane_b32 v255, s2, 2
	s_add_i32 s2, 0, 0x1e020
	v_writelane_b32 v255, s2, 3
	s_add_i32 s2, 0, 0x1e820
	v_writelane_b32 v255, s2, 4
	s_add_i32 s2, 0, 0x1e3a0
	s_mul_i32 s1, s77, s76
	v_writelane_b32 v255, s2, 5
	s_waitcnt lgkmcnt(0)
	s_mul_i32 s77, s1, s0
	v_writelane_b32 v255, s97, 6
	s_add_i32 s84, 0, 0x23fc0
	v_writelane_b32 v255, s77, 7
	s_add_i32 s85, 0, 0x23fc4
	v_writelane_b32 v255, s84, 8
	s_mov_b32 s81, 0
	s_mov_b64 s[12:13], -1
	s_movk_i32 s68, 0xb00
	s_movk_i32 s0, 0x2000
	s_mov_b32 s69, 0x1fffe0
	s_movk_i32 s70, 0x161
	s_mov_b32 s71, 0x10000
	v_mov_b32_e32 v0, 0
	s_mov_b64 s[72:73], 0x40000
	s_movk_i32 s1, 0x3c0
	s_mov_b32 s74, 0x18000
	s_mov_b64 s[94:95], 0x80
	s_mov_b32 s75, 0x8000
	s_movk_i32 s82, 0x80
	v_mov_b32_e32 v219, 0x358637bd
	s_mov_b32 s86, 0x800000
	s_movk_i32 s83, 0x1600
	s_mov_b64 s[90:91], 0x10000
	v_mov_b32_e32 v254, 0x2000
	v_mov_b32_e32 v225, 0x13000
	v_mov_b32_e32 v253, 1
	s_mov_b32 s87, 0x40000
	s_mov_b32 s92, 0x48000
	s_mov_b32 s93, 0x50000
	s_movk_i32 s33, 0x1000
	s_movk_i32 s88, 0x3000
	s_movk_i32 s89, 0x101
	v_mov_b32_e32 v224, 0x260
	v_mov_b64_e32 v[200:201], 0x200
	v_mov_b64_e32 v[202:203], 0x1ff
	v_mov_b32_e32 v226, 0x80
	v_mov_b32_e32 v227, 0xfe0
	s_mov_b32 s6, 0
	s_mov_b32 s96, 0x3e38aa3b
	v_writelane_b32 v255, s85, 9
	s_branch .LBB0_102

.LBB0_145:
	s_waitcnt vmcnt(0)
	v_mov_b32_e32 v1, v218
	s_waitcnt vmcnt(0) lgkmcnt(0)
	s_barrier
	s_nop 0
	v_cmp_eq_u32_e32 vcc, 0, v1
	s_and_saveexec_b64 s[2:3], vcc
	s_cbranch_execz .LBB0_197
	v_readlane_b32 s101, v255, 12
	s_nop 3
	s_cmp_eq_u32 s101, 0
	s_cbranch_scc1 .Lfb_slow_1
	v_readlane_b32 s100, v255, 40
	s_nop 3
	s_cmp_eq_u32 s100, 0
	s_cbranch_scc1 .Lfb_slow_1
	v_readlane_b32 s100, v255, 41
	v_readlane_b32 s101, v255, 42
	v_readlane_b32 vcc_lo, v255, 47
	v_mov_b32_e32 v2, 0
	v_mov_b32_e32 v4, 1
	s_nop 1
	s_add_i32 vcc_lo, vcc_lo, 1
	s_lshl_b32 vcc_hi, vcc_lo, 5
	v_writelane_b32 v255, vcc_lo, 47
	global_atomic_add v2, v4, s[100:101]
.Lfb_spin_1:
	global_load_dword v3, v2, s[100:101] sc1
	s_waitcnt vmcnt(0)
	v_readfirstlane_b32 vcc_lo, v3
	s_nop 3
	s_cmp_ge_u32 vcc_lo, vcc_hi
	s_cbranch_scc1 .Lfb_done_1
	s_sleep 1
	s_branch .Lfb_spin_1

.Lsp_noF_2:
	v_cmp_eq_u32_e32 vcc, 0, v1
	s_and_saveexec_b64 s[2:3], vcc
	s_cbranch_execz .LBB0_315
	v_readlane_b32 s100, v255, 40
	s_nop 3
	s_cmp_eq_u32 s100, 0
	s_cbranch_scc1 .Lfb_slow_2
	v_readlane_b32 s100, v255, 41
	v_readlane_b32 s101, v255, 42
	v_readlane_b32 vcc_lo, v255, 47
	v_mov_b32_e32 v2, 0
	v_mov_b32_e32 v4, 1
	s_nop 1
	s_add_i32 vcc_lo, vcc_lo, 1
	s_lshl_b32 vcc_hi, vcc_lo, 5
	v_writelane_b32 v255, vcc_lo, 47
	global_atomic_add v2, v4, s[100:101]

.Lfb_done_2:
	v_readlane_b32 vcc_lo, v255, 6
	s_nop 3
	s_lshr_b32 vcc_lo, vcc_lo, 3
	s_cmp_lg_u32 vcc_lo, 0
	s_cbranch_scc1 .Lsp_nolead_2
	buffer_wbl2 sc1
	s_waitcnt vmcnt(0)
	v_readlane_b32 s100, v255, 45
	v_readlane_b32 s101, v255, 46
	s_nop 4
	global_atomic_add v2, v4, s[100:101]

.LBB0_440:
	s_waitcnt vmcnt(0)
	v_mov_b32_e32 v1, v218
	s_waitcnt lgkmcnt(0)
	s_barrier
	s_nop 0
	v_cmp_eq_u32_e32 vcc, 0, v1
	s_and_saveexec_b64 s[2:3], vcc
	s_mov_b32 s1, 0x7f807f81
	s_movk_i32 s50, 0x5b
	s_mov_b32 s51, 0xf800000
	s_mov_b32 s52, 0x3fb8aa3b
	s_cbranch_execz .LBB0_492
	v_readlane_b32 s100, v255, 40
	s_nop 3
	s_cmp_eq_u32 s100, 0
	s_cbranch_scc1 .Lfb_slow_3
	v_readlane_b32 s100, v255, 41
	v_readlane_b32 s101, v255, 42
	v_readlane_b32 vcc_lo, v255, 47
	v_mov_b32_e32 v2, 0
	v_mov_b32_e32 v4, 1
	s_nop 1
	s_add_i32 vcc_lo, vcc_lo, 1
	s_lshl_b32 vcc_hi, vcc_lo, 5
	v_writelane_b32 v255, vcc_lo, 47
	global_atomic_add v2, v4, s[100:101]

.LBB0_742:
	s_waitcnt lgkmcnt(0)
	s_barrier
	s_waitcnt vmcnt(0)
	v_mov_b32_e32 v1, v218
	s_barrier
	s_nop 0
	v_cmp_eq_u32_e32 vcc, 0, v1
	s_and_saveexec_b64 s[2:3], vcc
	v_readlane_b32 s78, v255, 0
	v_readlane_b32 s79, v255, 1
	s_load_dwordx2 s[76:77], s[78:79], 0x100
	v_readlane_b32 s48, v255, 17
	v_readlane_b32 s97, v255, 6
	s_waitcnt lgkmcnt(0)
	v_readlane_b32 s77, v255, 7
	s_mov_b32 s69, 0x1fffe0
	s_mov_b32 s71, 0x10000
	s_mov_b32 s81, s87
	s_movk_i32 s0, 0x2000
	s_mov_b64 s[72:73], 0x40000
	s_movk_i32 s1, 0x3c0
	s_mov_b32 s74, 0x18000
	s_mov_b32 s75, 0x8000
	v_readlane_b32 s84, v255, 8
	v_readlane_b32 s85, v255, 9
	s_mov_b64 s[90:91], 0x10000
	s_mov_b32 s87, 0x40000
	s_mov_b32 s92, 0x48000
	s_mov_b32 s93, 0x50000
	v_readlane_b32 s50, v255, 19
	v_readlane_b32 s51, v255, 20
	v_readlane_b32 s49, v255, 18
	s_cbranch_execz .LBB0_794
	v_readlane_b32 s100, v255, 40
	s_nop 3
	s_cmp_eq_u32 s100, 0
	s_cbranch_scc1 .Lfb_slow_4
	v_readlane_b32 s100, v255, 41
	v_readlane_b32 s101, v255, 42
	v_readlane_b32 vcc_lo, v255, 47
	v_mov_b32_e32 v2, 0
	v_mov_b32_e32 v4, 1
	s_nop 1
	s_add_i32 vcc_lo, vcc_lo, 1
	s_lshl_b32 vcc_hi, vcc_lo, 5
	v_writelane_b32 v255, vcc_lo, 47
	global_atomic_add v2, v4, s[100:101]

.LBB0_818:
	s_waitcnt vmcnt(0)
	v_mov_b32_e32 v1, v218
	s_waitcnt lgkmcnt(0)
	s_barrier
	s_nop 0
	v_cmp_eq_u32_e32 vcc, 0, v1
	s_and_saveexec_b64 s[2:3], vcc
	s_xor_b64 s[2:3], exec, s[2:3]
	s_cbranch_execz .LBB0_871
	v_readlane_b32 s100, v255, 40
	s_nop 3
	s_cmp_eq_u32 s100, 0
	s_cbranch_scc1 .Lfb_slow_5
	v_readlane_b32 s100, v255, 41
	v_readlane_b32 s101, v255, 42
	v_readlane_b32 vcc_lo, v255, 47
	v_mov_b32_e32 v2, 0
	v_mov_b32_e32 v4, 1
	s_nop 1
	s_add_i32 vcc_lo, vcc_lo, 1
	s_lshl_b32 vcc_hi, vcc_lo, 5
	v_writelane_b32 v255, vcc_lo, 47
	global_atomic_add v2, v4, s[100:101]

.LBB0_913:
	s_waitcnt vmcnt(0)
	v_mov_b32_e32 v1, v218
	s_waitcnt lgkmcnt(0)
	s_barrier
	s_nop 0
	v_cmp_eq_u32_e32 vcc, 0, v1
	s_and_saveexec_b64 s[2:3], vcc
	s_cbranch_execz .LBB0_965
	v_readlane_b32 s100, v255, 40
	s_nop 3
	s_cmp_eq_u32 s100, 0
	s_cbranch_scc1 .Lfb_slow_6
	v_readlane_b32 s100, v255, 41
	v_readlane_b32 s101, v255, 42
	v_readlane_b32 vcc_lo, v255, 47
	v_mov_b32_e32 v2, 0
	v_mov_b32_e32 v4, 1
	s_nop 1
	s_add_i32 vcc_lo, vcc_lo, 1
	s_lshl_b32 vcc_hi, vcc_lo, 5
	v_writelane_b32 v255, vcc_lo, 47
	global_atomic_add v2, v4, s[100:101]

.LBB0_1287:
	v_readlane_b32 s101, v255, 12
	s_nop 3
	s_cmp_lg_u32 s101, 0
	s_cbranch_scc1 .Lfb_slow_10
	v_readlane_b32 s100, v255, 40
	s_nop 3
	s_cmp_eq_u32 s100, 0
	s_cbranch_scc1 .Lfb_slow_10
	v_readlane_b32 s100, v255, 41
	v_readlane_b32 s101, v255, 42
	v_readlane_b32 vcc_lo, v255, 47
	v_mov_b32_e32 v2, 0
	v_mov_b32_e32 v4, 1
	s_nop 1
	s_add_i32 vcc_lo, vcc_lo, 1
	s_lshl_b32 vcc_hi, vcc_lo, 5
	v_writelane_b32 v255, vcc_lo, 47
	global_atomic_add v2, v4, s[100:101]
